# attention: the rare O-rescale block returns immediately on the first tile of an item (O is still zero there); check placed in the out-of-line block, hot loop unchanged
# speedup vs baseline: 1.0042x; 1.0015x over previous
.LA_slow0:
	s_cmp_eq_u32 s16, 0
	s_cbranch_scc1 .LA_rs0
	s_and_saveexec_b64 s[60:61], s[4:5]
	ds_write_b32 v234, v215 offset:128
	s_or_b64 exec, exec, s[60:61]
	s_waitcnt lgkmcnt(0)
	v_add_u32_e32 v245, v232, v233
	ds_read_b128 v[220:223], v245 offset:224
	ds_read_b128 v[224:227], v245 offset:192
	ds_read_b128 v[216:219], v245 offset:160
	ds_read_b128 v[212:215], v245 offset:128
	s_waitcnt lgkmcnt(0)
	v_mul_f32_e32 v12, v12, v220
	v_mul_f32_e32 v13, v13, v221
	v_mul_f32_e32 v14, v14, v222
	v_mul_f32_e32 v15, v15, v223
	v_mul_f32_e32 v8, v8, v224
	v_mul_f32_e32 v9, v9, v225
	v_mul_f32_e32 v10, v10, v226
	v_mul_f32_e32 v11, v11, v227
	v_mul_f32_e32 v4, v4, v216
	v_mul_f32_e32 v5, v5, v217
	v_mul_f32_e32 v6, v6, v218
	v_mul_f32_e32 v7, v7, v219
	v_mul_f32_e32 v0, v0, v212
	v_mul_f32_e32 v1, v1, v213
	v_mul_f32_e32 v2, v2, v214
	v_mul_f32_e32 v3, v3, v215
	v_mul_f32_e32 v28, v28, v220
	v_mul_f32_e32 v29, v29, v221
	v_mul_f32_e32 v30, v30, v222
	v_mul_f32_e32 v31, v31, v223
	v_mul_f32_e32 v24, v24, v224
	v_mul_f32_e32 v25, v25, v225
	v_mul_f32_e32 v26, v26, v226
	v_mul_f32_e32 v27, v27, v227
	v_mul_f32_e32 v20, v20, v216
	v_mul_f32_e32 v21, v21, v217
	v_mul_f32_e32 v22, v22, v218
	v_mul_f32_e32 v23, v23, v219
	v_mul_f32_e32 v16, v16, v212
	v_mul_f32_e32 v17, v17, v213
	v_mul_f32_e32 v18, v18, v214
	v_mul_f32_e32 v19, v19, v215
	s_nop 1
	s_branch .LA_rs0
.LA_slow1:
	s_cmp_eq_u32 s16, 0
	s_cbranch_scc1 .LA_rs1
	s_and_saveexec_b64 s[60:61], s[4:5]
	ds_write_b32 v234, v215 offset:128
	s_or_b64 exec, exec, s[60:61]
	s_waitcnt lgkmcnt(0)
	v_add_u32_e32 v245, v232, v233
	ds_read_b128 v[220:223], v245 offset:224
	ds_read_b128 v[224:227], v245 offset:192
	ds_read_b128 v[216:219], v245 offset:160
	ds_read_b128 v[212:215], v245 offset:128
	s_waitcnt lgkmcnt(0)
	v_mul_f32_e32 v44, v44, v220
	v_mul_f32_e32 v45, v45, v221
	v_mul_f32_e32 v46, v46, v222
	v_mul_f32_e32 v47, v47, v223
	v_mul_f32_e32 v40, v40, v224
	v_mul_f32_e32 v41, v41, v225
	v_mul_f32_e32 v42, v42, v226
	v_mul_f32_e32 v43, v43, v227
	v_mul_f32_e32 v36, v36, v216
	v_mul_f32_e32 v37, v37, v217
	v_mul_f32_e32 v38, v38, v218
	v_mul_f32_e32 v39, v39, v219
	v_mul_f32_e32 v32, v32, v212
	v_mul_f32_e32 v33, v33, v213
	v_mul_f32_e32 v34, v34, v214
	v_mul_f32_e32 v35, v35, v215
	v_mul_f32_e32 v60, v60, v220
	v_mul_f32_e32 v61, v61, v221
	v_mul_f32_e32 v62, v62, v222
	v_mul_f32_e32 v63, v63, v223
	v_mul_f32_e32 v56, v56, v224
	v_mul_f32_e32 v57, v57, v225
	v_mul_f32_e32 v58, v58, v226
	v_mul_f32_e32 v59, v59, v227
	v_mul_f32_e32 v52, v52, v216
	v_mul_f32_e32 v53, v53, v217
	v_mul_f32_e32 v54, v54, v218
	v_mul_f32_e32 v55, v55, v219
	v_mul_f32_e32 v48, v48, v212
	v_mul_f32_e32 v49, v49, v213
	v_mul_f32_e32 v50, v50, v214
	v_mul_f32_e32 v51, v51, v215
	s_nop 1
	s_branch .LA_rs1
